# prompt forgetting attention: K/V staged two 128-key steps ahead in two register sets (parity-selected), counted wait before LDS write
# baseline (speedup 1.0000x reference)
.LBB0_575:
	s_or_b64 exec, exec, s[4:5]
	v_lshlrev_b32_e32 v200, 11, v196
	v_mov_b32_e32 v201, 0
	v_or_b32_e32 v2, 1, v196
	v_lshlrev_b32_e32 v202, 11, v2
	v_mov_b32_e32 v203, 0
	v_or_b32_e32 v2, 2, v196
	v_lshlrev_b32_e32 v204, 11, v2
	v_mov_b32_e32 v205, 0
	v_or_b32_e32 v2, 3, v196
	v_lshlrev_b32_e32 v206, 11, v2
	v_mov_b32_e32 v207, 0
	v_add_u32_e32 v208, 0x4000, v200
	v_mov_b32_e32 v209, 0
	v_add_u32_e32 v210, 0x4800, v200
	v_mov_b32_e32 v211, 0
	v_add_u32_e32 v212, 0x5000, v200
	v_mov_b32_e32 v213, 0
	v_add_u32_e32 v214, 0x5800, v200
	v_mov_b32_e32 v215, 0
	s_waitcnt lgkmcnt(0)
	ds_read_b128 v[2:5], v246
	ds_read_b128 v[6:9], v246 offset:32
	s_lshl_b64 s[4:5], s[42:43], 11
	v_lshl_add_u64 v[10:11], v[198:199], 0, s[4:5]
	v_lshl_add_u64 v[12:13], v[10:11], 0, v[200:201]
	s_waitcnt lgkmcnt(1)
	v_mul_f32_e32 v0, v32, v2
	v_cvt_pk_bf16_f32 v0, v0, s0
	global_store_short v[12:13], v0, off
	v_mul_f32_e32 v0, v16, v2
	v_cvt_pk_bf16_f32 v0, v0, s0
	global_store_short v[12:13], v0, off offset:64
	v_mul_f32_e32 v0, v33, v3
	v_cvt_pk_bf16_f32 v0, v0, s0
	v_lshl_add_u64 v[12:13], v[10:11], 0, v[202:203]
	global_store_short v[12:13], v0, off
	v_mul_f32_e32 v0, v17, v3
	v_cvt_pk_bf16_f32 v0, v0, s0
	global_store_short v[12:13], v0, off offset:64
	v_mul_f32_e32 v0, v34, v4
	v_cvt_pk_bf16_f32 v0, v0, s0
	v_lshl_add_u64 v[2:3], v[10:11], 0, v[204:205]
	global_store_short v[2:3], v0, off
	v_mul_f32_e32 v0, v18, v4
	v_cvt_pk_bf16_f32 v0, v0, s0
	global_store_short v[2:3], v0, off offset:64
	v_mul_f32_e32 v0, v35, v5
	v_cvt_pk_bf16_f32 v0, v0, s0
	v_lshl_add_u64 v[2:3], v[10:11], 0, v[206:207]
	global_store_short v[2:3], v0, off
	v_mul_f32_e32 v0, v19, v5
	v_cvt_pk_bf16_f32 v0, v0, s0
	global_store_short v[2:3], v0, off offset:64
	s_waitcnt lgkmcnt(0)
	v_mul_f32_e32 v0, v36, v6
	v_cvt_pk_bf16_f32 v0, v0, s0
	v_lshl_add_u64 v[2:3], v[10:11], 0, v[208:209]
	global_store_short v[2:3], v0, off
	v_mul_f32_e32 v0, v20, v6
	v_cvt_pk_bf16_f32 v0, v0, s0
	global_store_short v[2:3], v0, off offset:64
	v_mul_f32_e32 v0, v37, v7
	v_cvt_pk_bf16_f32 v0, v0, s0
	v_lshl_add_u64 v[2:3], v[10:11], 0, v[210:211]
	global_store_short v[2:3], v0, off
	v_mul_f32_e32 v0, v21, v7
	v_cvt_pk_bf16_f32 v0, v0, s0
	global_store_short v[2:3], v0, off offset:64
	v_mul_f32_e32 v0, v38, v8
	v_cvt_pk_bf16_f32 v0, v0, s0
	v_lshl_add_u64 v[2:3], v[10:11], 0, v[212:213]
	global_store_short v[2:3], v0, off
	v_mul_f32_e32 v0, v22, v8
	v_cvt_pk_bf16_f32 v0, v0, s0
	global_store_short v[2:3], v0, off offset:64
	v_mul_f32_e32 v0, v39, v9
	v_cvt_pk_bf16_f32 v0, v0, s0
	v_lshl_add_u64 v[2:3], v[10:11], 0, v[214:215]
	global_store_short v[2:3], v0, off
	v_mul_f32_e32 v0, v23, v9
	v_cvt_pk_bf16_f32 v0, v0, s0
	global_store_short v[2:3], v0, off offset:64
	ds_read_b128 v[2:5], v246 offset:64
	ds_read_b128 v[6:9], v246 offset:96
	v_lshl_add_u64 v[12:13], v[10:11], 0, v[216:217]
	s_add_i32 s18, s18, 1
	s_addk_i32 s19, 0x100
	s_waitcnt lgkmcnt(1)
	v_mul_f32_e32 v0, v40, v2
	v_cvt_pk_bf16_f32 v0, v0, s0
	global_store_short v[12:13], v0, off
	v_mul_f32_e32 v0, v24, v2
	v_cvt_pk_bf16_f32 v0, v0, s0
	global_store_short v[12:13], v0, off offset:64
	v_mul_f32_e32 v0, v41, v3
	v_cvt_pk_bf16_f32 v0, v0, s0
	v_lshl_add_u64 v[12:13], v[10:11], 0, v[218:219]
	global_store_short v[12:13], v0, off
	v_mul_f32_e32 v0, v25, v3
	v_cvt_pk_bf16_f32 v0, v0, s0
	global_store_short v[12:13], v0, off offset:64
	v_mul_f32_e32 v0, v42, v4
	v_cvt_pk_bf16_f32 v0, v0, s0
	v_lshl_add_u64 v[2:3], v[10:11], 0, v[220:221]
	global_store_short v[2:3], v0, off
	v_mul_f32_e32 v0, v26, v4
	v_cvt_pk_bf16_f32 v0, v0, s0
	global_store_short v[2:3], v0, off offset:64
	v_mul_f32_e32 v0, v43, v5
	v_cvt_pk_bf16_f32 v0, v0, s0
	v_lshl_add_u64 v[2:3], v[10:11], 0, v[222:223]
	global_store_short v[2:3], v0, off
	v_mul_f32_e32 v0, v27, v5
	v_cvt_pk_bf16_f32 v0, v0, s0
	global_store_short v[2:3], v0, off offset:64
	s_waitcnt lgkmcnt(0)
	v_mul_f32_e32 v0, v44, v6
	v_cvt_pk_bf16_f32 v0, v0, s0
	v_lshl_add_u64 v[2:3], v[10:11], 0, v[224:225]
	global_store_short v[2:3], v0, off
	v_mul_f32_e32 v0, v28, v6
	v_cvt_pk_bf16_f32 v0, v0, s0
	global_store_short v[2:3], v0, off offset:64
	v_mul_f32_e32 v0, v45, v7
	v_cvt_pk_bf16_f32 v0, v0, s0
	v_lshl_add_u64 v[2:3], v[10:11], 0, v[226:227]
	global_store_short v[2:3], v0, off
	v_mul_f32_e32 v0, v29, v7
	v_cvt_pk_bf16_f32 v0, v0, s0
	global_store_short v[2:3], v0, off offset:64
	v_mul_f32_e32 v0, v46, v8
	v_cvt_pk_bf16_f32 v0, v0, s0
	v_lshl_add_u64 v[2:3], v[10:11], 0, v[228:229]
	global_store_short v[2:3], v0, off
	v_mul_f32_e32 v0, v30, v8
	v_cvt_pk_bf16_f32 v0, v0, s0
	global_store_short v[2:3], v0, off offset:64
	v_mul_f32_e32 v0, v47, v9
	v_cvt_pk_bf16_f32 v0, v0, s0
	v_lshl_add_u64 v[2:3], v[10:11], 0, v[230:231]
	global_store_short v[2:3], v0, off
	v_mul_f32_e32 v0, v31, v9
	v_cvt_pk_bf16_f32 v0, v0, s0
	v_add_u32_e32 v248, 0x100, v248
	s_cmp_eq_u32 s18, 8
	global_store_short v[2:3], v0, off offset:64
	s_cbranch_scc1 .LBB0_452

.LBB0_579:
	s_lshl_b32 s14, s18, 2
	s_add_i32 s14, s14, -8
	s_ashr_i32 s14, s14, 1
	s_cmp_gt_u32 s18, 2
	s_cselect_b32 s16, s14, 0
	s_and_b64 s[14:15], exec, s[6:7]
	s_cselect_b32 s20, 0, s16
	s_lshl_b32 s21, s20, 7
	v_add_u32_e32 v2, s21, v241
	v_ashrrev_i32_e32 v3, 31, v2
	v_lshlrev_b64 v[2:3], 7, v[2:3]
	v_lshl_or_b32 v2, v194, 1, v2
	v_lshl_add_u64 v[4:5], s[10:11], 0, v[2:3]
	v_add_co_u32_e32 v6, vcc, s0, v4
	v_lshl_add_u64 v[2:3], s[12:13], 0, v[2:3]
	s_nop 0
	v_addc_co_u32_e32 v7, vcc, 0, v5, vcc
	global_load_dwordx4 v[100:103], v[4:5], off
	global_load_dwordx4 v[104:107], v[6:7], off
	global_load_dwordx4 v[108:111], v[2:3], off
	v_add_co_u32_e32 v2, vcc, 0x2000, v2
	s_lshl_b32 s23, s18, 1
	s_nop 0
	v_addc_co_u32_e32 v3, vcc, 0, v3, vcc
	global_load_dwordx4 v[112:115], v[2:3], off
	s_or_b32 s14, s23, 1
	s_mov_b32 s22, 0
	s_cmp_gt_i32 s20, s14
	s_waitcnt vmcnt(0)
	ds_write_b128 v242, v[100:103]
	ds_write_b128 v242, v[108:111] offset:36864
	ds_write_b128 v242, v[104:107] offset:9216
	ds_write_b128 v242, v[112:115] offset:46080
	s_cmp_le_i32 s20, s23
	s_cbranch_scc0 .Lkvb_pro_skip
	v_add_u32_e32 v2, s21, v241
	v_add_u32_e32 v2, 0x80, v2
	v_ashrrev_i32_e32 v3, 31, v2
	v_lshlrev_b64 v[2:3], 7, v[2:3]
	v_lshl_or_b32 v2, v194, 1, v2
	v_lshl_add_u64 v[4:5], s[10:11], 0, v[2:3]
	v_add_co_u32_e32 v6, vcc, 0x2000, v4
	v_lshl_add_u64 v[2:3], s[12:13], 0, v[2:3]
	s_nop 0
	v_addc_co_u32_e32 v7, vcc, 0, v5, vcc
	global_load_dwordx4 v[200:203], v[4:5], off
	global_load_dwordx4 v[204:207], v[6:7], off
	v_add_co_u32_e32 v4, vcc, 0x2000, v2
	s_nop 1
	v_addc_co_u32_e32 v5, vcc, 0, v3, vcc
	global_load_dwordx4 v[208:211], v[2:3], off
	global_load_dwordx4 v[212:215], v[4:5], off
.Lkvb_pro_skip:
	s_cmp_gt_i32 s20, s14
	s_waitcnt lgkmcnt(0)
	s_barrier
	s_cbranch_scc1 .LBB0_614
	s_lshr_b32 s36, s42, 6
	v_sub_u32_e64 v2, s36, 8 clamp
	s_and_b64 s[14:15], exec, s[6:7]
	v_add_f32_e32 v0, v239, v0
	v_readfirstlane_b32 s14, v2
	v_xor_b32_e32 v2, 0x80000000, v0
	v_cvt_pk_bf16_f32 v2, v2, 0
	v_lshlrev_b32_e32 v2, 16, v2
	v_sub_f32_e64 v0, -v0, v2
	v_or_b32_e32 v3, 0x3f80, v2
	v_cvt_pk_bf16_f32 v2, v0, 0
	v_and_b32_e32 v4, 0xffff, v2
	v_lshlrev_b32_e32 v2, 16, v2
	v_sub_f32_e32 v0, v0, v2
	v_cvt_pk_bf16_f32 v0, v0, 0
	v_lshl_or_b32 v0, v0, 16, v4
	v_mov_b32_e32 v14, v1
	v_mov_b32_e32 v15, v1
	v_cndmask_b32_e64 v82, 0, v0, s[2:3]
	v_cndmask_b32_e64 v81, 0, v3, s[2:3]
	v_mov_b32_e32 v0, v1
	v_mov_b32_e32 v2, v1
	v_mov_b32_e32 v3, v1
	v_mov_b32_e32 v4, v1
	v_mov_b32_e32 v5, v1
	v_mov_b32_e32 v6, v1
	v_mov_b32_e32 v7, v1
	v_mov_b32_e32 v8, v1
	v_mov_b32_e32 v9, v1
	v_mov_b32_e32 v10, v1
	v_mov_b32_e32 v11, v1
	v_mov_b32_e32 v12, v1
	v_mov_b32_e32 v13, v1
	v_mov_b64_e32 v[46:47], v[14:15]
	v_mov_b64_e32 v[30:31], v[14:15]
	s_cselect_b32 s37, 0, s14
	v_mov_b32_e32 v83, v1
	v_subrev_u32_e32 v251, 32, v232
	v_lshl_add_u32 v252, s20, 10, v247
	s_sub_i32 s40, 0, s21
	s_lshl_b32 s41, s20, 1
	v_mov_b32_e32 v233, 0
	s_mov_b32 s63, s19
	v_mov_b32_e32 v253, v248
	v_mov_b32_e32 v254, v196
	s_mov_b32 s96, 0
	v_add_u32_e32 v197, 0x80, v241
	v_mov_b64_e32 v[44:45], v[12:13]
	v_mov_b64_e32 v[42:43], v[10:11]
	v_mov_b64_e32 v[40:41], v[8:9]
	v_mov_b64_e32 v[38:39], v[6:7]
	v_mov_b64_e32 v[36:37], v[4:5]
	v_mov_b64_e32 v[34:35], v[2:3]
	v_mov_b64_e32 v[32:33], v[0:1]
	v_mov_b64_e32 v[28:29], v[12:13]
	v_mov_b64_e32 v[26:27], v[10:11]
	v_mov_b64_e32 v[24:25], v[8:9]
	v_mov_b64_e32 v[22:23], v[6:7]
	v_mov_b64_e32 v[20:21], v[4:5]
	v_mov_b64_e32 v[18:19], v[2:3]
	v_mov_b64_e32 v[16:17], v[0:1]
	s_branch .LBB0_582

.LBB0_582:
	s_add_i32 s16, s20, s22
	s_cmp_le_i32 s16, s23
	s_cselect_b64 s[14:15], -1, 0
	s_mov_b32 s32, 0
	s_cmp_ge_i32 s16, s23
	s_cbranch_scc1 .LBB0_584
	s_mov_b32 s32, 1
	v_add_u32_e32 v2, s21, v197
	v_add_u32_e32 v2, 0x80, v2
	v_ashrrev_i32_e32 v3, 31, v2
	v_lshlrev_b64 v[2:3], 7, v[2:3]
	v_lshl_or_b32 v2, v194, 1, v2
	v_lshl_add_u64 v[4:5], s[10:11], 0, v[2:3]
	v_add_co_u32_e32 v6, vcc, 0x2000, v4
	v_lshl_add_u64 v[2:3], s[12:13], 0, v[2:3]
	s_nop 0
	v_addc_co_u32_e32 v7, vcc, 0, v5, vcc
	s_bitcmp1_b32 s22, 0
	s_cbranch_scc1 .Lkvb_ld_odd
	global_load_dwordx4 v[100:103], v[4:5], off
	global_load_dwordx4 v[104:107], v[6:7], off
	v_add_co_u32_e32 v4, vcc, 0x2000, v2
	s_nop 1
	v_addc_co_u32_e32 v5, vcc, 0, v3, vcc
	global_load_dwordx4 v[108:111], v[2:3], off
	global_load_dwordx4 v[112:115], v[4:5], off
	s_branch .LBB0_584
.Lkvb_ld_odd:
	global_load_dwordx4 v[200:203], v[4:5], off
	global_load_dwordx4 v[204:207], v[6:7], off
	v_add_co_u32_e32 v4, vcc, 0x2000, v2
	s_nop 1
	v_addc_co_u32_e32 v5, vcc, 0, v3, vcc
	global_load_dwordx4 v[208:211], v[2:3], off
	global_load_dwordx4 v[212:215], v[4:5], off

.LBB0_612:
	s_andn2_b64 vcc, exec, s[14:15]
	s_cbranch_vccnz .LBB0_581
	s_xor_b32 s14, s97, 1
	s_mulk_i32 s14, 0x4800
	v_add_u32_e32 v0, s14, v242
	s_cmp_eq_u32 s32, 0
	s_cbranch_scc1 .Lkvb_w0
	s_waitcnt vmcnt(4)
	s_branch .Lkvb_w1

.Lkvb_w1:
	s_bitcmp1_b32 s22, 0
	s_cbranch_scc1 .Lkvb_st_odd
	ds_write_b128 v0, v[200:203]
	ds_write_b128 v0, v[204:207] offset:9216
	ds_write_b128 v0, v[208:211] offset:36864
	ds_write_b128 v0, v[212:215] offset:46080
	s_branch .LBB0_581
.Lkvb_st_odd:
	ds_write_b128 v0, v[100:103]
	ds_write_b128 v0, v[104:107] offset:9216
	ds_write_b128 v0, v[108:111] offset:36864
	ds_write_b128 v0, v[112:115] offset:46080
	s_branch .LBB0_581
